# gate g-loop software-pipelined: next group's loads issued before the current group's gating stage, u/gate_b prefetched one group ahead
# speedup vs baseline: 1.0251x; 1.0029x over previous
; __device__ __forceinline__ float bf_lo(unsigned w) { return __uint_as_float(w << 16); }
; #define LAS __attribute__((address_space(3)))
; __device__ __forceinline__ void gate_unit(LAS unsigned char* lds, bf16_t* Zg, int ch, const bf16_t* wsb, const float* ln_g, const float* ln_b, const float* b_s, bool dostore = true) {
;     ...
;     const int pt = wid >> 1, kt0 = 2 * (wid & 1);
;     for (int g = 0; g < 8; ++g) {
; #pragma unroll
;         for (int i = 0; i < 4; ++i) { const int p = tid + 512 * i, q = p >> 4, c = p & 15; const int col = g * 128 + c * 8;
;             const u32x4 w = *(const u32x4*)(Zc + (size_t)q * ZLD + COL_VB + col);
;             const float mean = stats[q * 2], rstd = stats[q * 2 + 1];
;             const f32x4 g0 = *(const f32x4*)(ln_g + col), g1 = *(const f32x4*)(ln_g + col + 4), b0 = *(const f32x4*)(ln_b + col), b1 = *(const f32x4*)(ln_b + col + 4);
;             float v[8] = {bf_lo(w.x), bf_hi(w.x), bf_lo(w.y), bf_hi(w.y), bf_lo(w.z), bf_hi(w.z), bf_lo(w.w), bf_hi(w.w)};
;             const float gg[8] = {g0.x, g0.y, g0.z, g0.w, g1.x, g1.y, g1.z, g1.w}, bb[8] = {b0.x, b0.y, b0.z, b0.w, b1.x, b1.y, b1.z, b1.w};
; #pragma unroll
;             for (int e = 0; e < 8; ++e) vnT[(c * 8 + e) * 136 + q] = (bf16_t)f2bf((v[e] - mean) * rstd * gg[e] + bb[e]); }
;         __syncthreads();
;         f32x16 acc[2]; acc[0] = f32x16{}; acc[1] = f32x16{};
;         const bf16_t* ap = wsb + (size_t)g * 16384 + (32 * pt + r32) * 128 + 8 * hi;
; #pragma unroll
;         for (int ks = 0; ks < 8; ++ks) { const bf16x8 a = *(const bf16x8*)(ap + 16 * ks);
; #pragma unroll
;             for (int j = 0; j < 2; ++j) { const bf16x8 b = *(const LAS bf16x8*)(vnT + (32 * (kt0 + j) + r32) * 136 + 16 * ks + 8 * hi);
;                 acc[j] = __builtin_amdgcn_mfma_f32_32x32x16_bf16(a, b, acc[j], 0, 0, 0); } }
;         LAS float* st = (LAS float*)(lds + 40960);
; #pragma unroll
;         for (int j = 0; j < 2; ++j)
; #pragma unroll
;             for (int r = 0; r < 16; ++r) { const int p = 32 * pt + crow(r, hi); st[p * 132 + 32 * (kt0 + j) + r32] = acc[j][r] + b_s[g * 128 + p]; }
;         __syncthreads();
; #pragma unroll
;         for (int i = 0; i < 4; ++i) { const int p = (tid >> 4) + 32 * i, c8 = (tid & 15) * 8; bf16_t* zr = Zc + (size_t)p * ZLD + g * 128 + c8;
;             const u32x4 uw = *(const u32x4*)(zr + COL_U), gw = *(const u32x4*)(zr + COL_GB);
.LBB0_182:
	s_or_b64 exec, exec, s[74:75]
	v_lshlrev_b32_e32 v2, 3, v6
	s_lshr_b32 s4, s10, 5
	v_and_b32_e32 v4, 0x78, v2
	s_ashr_i32 s10, s10, 2
	v_ashrrev_i32_e32 v14, 4, v6
	v_lshrrev_b32_e32 v0, 5, v0
	s_and_b32 s16, s4, 2
	s_and_b32 s4, s10, 0xffffffe0
	v_lshl_add_u32 v37, v4, 2, 0
	v_lshl_add_u32 v36, v14, 3, 0
	v_lshl_or_b32 v34, v0, 2, s4
	s_waitcnt lgkmcnt(1)
	v_mad_u64_u32 v[2:3], s[4:5], v14, -6, v[36:37]
	v_mul_u32_u24_e32 v3, 0x110, v4
	v_add_u32_e32 v4, 0x200, v6
	v_ashrrev_i32_e32 v17, 4, v4
	v_lshl_add_u32 v38, v17, 3, 0
	s_waitcnt lgkmcnt(0)
	v_mad_u64_u32 v[4:5], s[4:5], v17, -6, v[38:39]
	v_add_u32_e32 v5, 0x400, v6
	v_ashrrev_i32_e32 v5, 4, v5
	v_lshl_add_u32 v40, v5, 3, 0
	v_mad_u64_u32 v[8:9], s[4:5], v5, -6, v[40:41]
	v_add_u32_e32 v9, 0x600, v6
	v_ashrrev_i32_e32 v9, 4, v9
	v_lshl_add_u32 v42, v9, 3, 0
	v_and_b32_e32 v7, 31, v6
	v_mad_u64_u32 v[10:11], s[4:5], v9, -6, v[42:43]
	v_lshl_add_u32 v16, v0, 4, 0
	v_lshl_add_u32 v0, v7, 2, 0
	s_or_b32 s4, s16, 1
	v_lshl_or_b32 v12, s4, 5, v7
	v_lshl_add_u32 v21, s4, 7, v0
	s_lshl_b32 s4, s10, 7
	s_and_b32 s4, s4, 0xfffff000
	v_mul_u32_u24_e32 v18, 0x110, v12
	v_lshl_or_b32 v12, v7, 7, s4
	v_lshl_add_u32 v19, s16, 7, v0
	v_and_b32_e32 v0, 32, v6
	v_ashrrev_i32_e32 v13, 31, v12
	v_lshrrev_b32_e32 v0, 1, v0
	v_lshlrev_b64 v[12:13], 1, v[12:13]
	v_or_b32_e32 v12, v12, v0
	v_lshl_add_u64 v[12:13], s[72:73], 0, v[12:13]
	s_mov_b64 s[4:5], 0x1800000
	v_lshl_add_u64 v[44:45], v[12:13], 0, s[4:5]
	v_mov_b64_e32 v[12:13], s[8:9]
	v_mul_lo_u32 v39, v14, s25
	v_mad_i64_i32 v[12:13], s[4:5], v14, s35, v[12:13]
	v_and_b32_e32 v14, 15, v6
	v_lshlrev_b32_e32 v0, 4, v14
	v_lshl_or_b32 v11, s16, 5, v7
	v_lshl_add_u64 v[6:7], v[12:13], 0, v[0:1]
	v_lshl_add_u64 v[46:47], s[26:27], 0, v[6:7]
	v_mov_b64_e32 v[6:7], s[6:7]
	v_mad_i64_i32 v[12:13], s[4:5], v9, s35, v[6:7]
	v_lshl_add_u64 v[12:13], v[12:13], 0, v[0:1]
	v_lshl_add_u64 v[48:49], s[26:27], 0, v[12:13]
	v_lshlrev_b32_e32 v12, 5, v14
	v_mov_b32_e32 v13, v1
	v_lshl_add_u64 v[14:15], s[70:71], 0, v[12:13]
	v_lshl_add_u64 v[50:51], v[14:15], 0, 16
	v_mad_i64_i32 v[14:15], s[4:5], v5, s35, v[6:7]
	v_mad_i64_i32 v[6:7], s[4:5], v17, s35, v[6:7]
	v_mul_u32_u24_e32 v11, 0x110, v11
	v_mul_lo_u32 v20, v34, s25
	v_add_u32_e32 v22, 0x8400, v39
	v_lshl_add_u64 v[14:15], v[14:15], 0, v[0:1]
	v_lshl_add_u64 v[12:13], s[68:69], 0, v[12:13]
	v_lshl_add_u64 v[6:7], v[6:7], 0, v[0:1]
	v_lshl_add_u64 v[52:53], s[26:27], 0, v[14:15]
	v_lshl_add_u64 v[54:55], v[12:13], 0, 16
	v_lshl_add_u64 v[56:57], s[26:27], 0, v[6:7]
	s_mov_b64 s[4:5], 0
	v_add_u32_e32 v0, v2, v3
	v_add_u32_e32 v41, v4, v3
	v_add_u32_e32 v43, v8, v3
	v_add_u32_e32 v62, v10, v3
	v_add_u32_e32 v63, v16, v11
	v_add_u32_e32 v64, v16, v18
	v_add_u32_e32 v65, v19, v20
	v_add_u32_e32 v66, v21, v20
	v_add_u32_e32 v67, v37, v22
	v_lshrrev_b32_e32 v176, 4, v204
	v_mul_u32_u24_e32 v176, 0x120, v176
	v_and_b32_e32 v177, 15, v204
	v_lshl_add_u32 v176, v177, 4, v176
	v_and_b32_e32 v177, 63, v204
	v_lshrrev_b32_e32 v178, 5, v177
	v_bfe_u32 v179, v177, 2, 2
	v_lshl_add_u32 v178, v178, 3, v179
	v_mul_u32_u24_e32 v178, 0x120, v178
	v_bfe_u32 v179, v177, 4, 1
	v_lshl_add_u32 v178, v179, 5, v178
	v_and_b32_e32 v179, 3, v177
	v_lshl_add_u32 v178, v179, 3, v178
	v_lshl_add_u32 v177, s16, 6, v178
	s_mov_b64 s[16:17], 0x8000
	v_lshl_add_u64 v[174:175], v[46:47], 0, s[4:5]
	v_add_co_u32_e32 v174, vcc, 0x5a02000, v174
	s_nop 1
	v_addc_co_u32_e32 v175, vcc, 0, v175, vcc
	global_load_dwordx4 v[190:193], v[174:175], off offset:2048
	v_lshl_add_u64 v[124:125], v[56:57], 0, s[4:5]
	global_load_dwordx4 v[80:83], v[124:125], off
	v_lshl_add_u64 v[124:125], v[52:53], 0, s[4:5]
	global_load_dwordx4 v[84:87], v[124:125], off
	v_lshl_add_u64 v[124:125], v[48:49], 0, s[4:5]
	global_load_dwordx4 v[88:91], v[124:125], off
	global_load_dwordx4 v[72:75], v[50:51], off
	global_load_dwordx4 v[68:71], v[50:51], off offset:-16
	global_load_dwordx4 v[186:189], v[54:55], off
	global_load_dwordx4 v[76:79], v[54:55], off offset:-16
	global_load_dwordx4 v[92:95], v[44:45], off
	global_load_dwordx4 v[96:99], v[44:45], off offset:32
	global_load_dwordx4 v[100:103], v[44:45], off offset:64
	global_load_dwordx4 v[104:107], v[44:45], off offset:96
	global_load_dwordx4 v[108:111], v[44:45], off offset:128
	global_load_dwordx4 v[112:115], v[44:45], off offset:160
	global_load_dwordx4 v[116:119], v[44:45], off offset:192
	global_load_dwordx4 v[120:123], v[44:45], off offset:224
	v_ashrrev_i32_e32 v35, 31, v34
	v_lshl_add_u64 v[124:125], v[34:35], 2, s[20:21]
	global_load_dwordx4 v[126:129], v[124:125], off
	global_load_dwordx4 v[130:133], v[124:125], off offset:32
	global_load_dwordx4 v[134:137], v[124:125], off offset:64
	global_load_dwordx4 v[138:141], v[124:125], off offset:96
	v_add_co_u32_e32 v124, vcc, 0x1000, v174
	s_nop 1
	v_addc_co_u32_e32 v125, vcc, 0, v175, vcc
	global_load_dwordx4 v[142:145], v[124:125], off offset:-4096
	global_load_dwordx4 v[146:149], v[124:125], off
	v_add_co_u32_e32 v124, vcc, 0x91000, v174
	s_nop 1
	v_addc_co_u32_e32 v125, vcc, 0, v175, vcc
	global_load_dwordx4 v[150:153], v[124:125], off offset:-4096
	global_load_dwordx4 v[154:157], v[124:125], off
	v_add_co_u32_e32 v124, vcc, 0x121000, v174
	s_nop 1
	v_addc_co_u32_e32 v125, vcc, 0, v175, vcc
	global_load_dwordx4 v[158:161], v[124:125], off offset:-4096
	global_load_dwordx4 v[162:165], v[124:125], off
	v_add_co_u32_e32 v124, vcc, 0x1b1000, v174
	s_nop 1
	v_addc_co_u32_e32 v125, vcc, 0, v175, vcc
	global_load_dwordx4 v[166:169], v[124:125], off offset:-4096
	global_load_dwordx4 v[170:173], v[124:125], off
	v_lshl_add_u64 v[50:51], v[50:51], 0, s[60:61]
	v_lshl_add_u64 v[54:55], v[54:55], 0, s[60:61]
	v_add_u32_e32 v34, 0x80, v34
	v_lshl_add_u64 v[44:45], v[44:45], 0, s[16:17]
	s_waitcnt vmcnt(0)
	s_barrier
; __device__ __forceinline__ float bf_lo(unsigned w) { return __uint_as_float(w << 16); }
; __device__ __forceinline__ float bf_hi(unsigned w) { return __uint_as_float(w & 0xffff0000u); }
; __device__ __forceinline__ unsigned f2bf(float f) { unsigned u = __builtin_bit_cast(unsigned, f); return (u + 0x7fffu + ((u >> 16) & 1u)) >> 16; }
; __device__ __forceinline__ void gate_unit(LAS unsigned char* lds, bf16_t* Zg, int ch, const bf16_t* wsb, const float* ln_g, const float* ln_b, const float* b_s, bool dostore = true) {
;     ...
;         for (int i = 0; i < 4; ++i) { const int p = tid + 512 * i, q = p >> 4, c = p & 15; const int col = g * 128 + c * 8;
;             const u32x4 w = *(const u32x4*)(Zc + (size_t)q * ZLD + COL_VB + col);
;             const float mean = stats[q * 2], rstd = stats[q * 2 + 1];
;             const f32x4 g0 = *(const f32x4*)(ln_g + col), g1 = *(const f32x4*)(ln_g + col + 4), b0 = *(const f32x4*)(ln_b + col), b1 = *(const f32x4*)(ln_b + col + 4);
;             float v[8] = {bf_lo(w.x), bf_hi(w.x), bf_lo(w.y), bf_hi(w.y), bf_lo(w.z), bf_hi(w.z), bf_lo(w.w), bf_hi(w.w)};
;             const float gg[8] = {g0.x, g0.y, g0.z, g0.w, g1.x, g1.y, g1.z, g1.w}, bb[8] = {b0.x, b0.y, b0.z, b0.w, b1.x, b1.y, b1.z, b1.w};
; #pragma unroll
;             for (int e = 0; e < 8; ++e) vnT[(c * 8 + e) * 136 + q] = (bf16_t)f2bf((v[e] - mean) * rstd * gg[e] + bb[e]); }
;         __syncthreads();
.LBB0_183:
	v_lshl_add_u64 v[58:59], v[46:47], 0, s[4:5]
	v_add_co_u32_e32 v60, vcc, 0x5a02000, v58
	ds_read_b64 v[22:23], v36
	s_nop 0
	v_addc_co_u32_e32 v61, vcc, 0, v59, vcc
	v_ashrrev_i32_e32 v35, 31, v34
	s_mov_b32 s10, 0x5a03000
	s_mov_b64 s[16:17], 0x8000
	ds_read_b64 v[180:181], v38
	ds_read_b64 v[182:183], v40
	ds_read_b64 v[184:185], v42
	s_waitcnt vmcnt(12) lgkmcnt(3)
	v_lshlrev_b32_e32 v24, 16, v190
	v_and_b32_e32 v25, 0xffff0000, v190
	v_sub_f32_e32 v24, v24, v22
	v_sub_f32_e32 v25, v25, v22
	v_mul_f32_e32 v24, v23, v24
	v_mul_f32_e32 v25, v23, v25
	v_fma_f32 v24, v68, v24, v76
	v_fma_f32 v25, v69, v25, v77
	v_cvt_pk_bf16_f32 v28, v24, v25
	v_lshlrev_b32_e32 v24, 16, v191
	v_and_b32_e32 v25, 0xffff0000, v191
	v_sub_f32_e32 v24, v24, v22
	v_sub_f32_e32 v25, v25, v22
	v_mul_f32_e32 v24, v23, v24
	v_mul_f32_e32 v25, v23, v25
	v_fma_f32 v24, v70, v24, v78
	v_fma_f32 v25, v71, v25, v79
	v_cvt_pk_bf16_f32 v29, v24, v25
	v_lshlrev_b32_e32 v24, 16, v192
	v_and_b32_e32 v25, 0xffff0000, v192
	v_sub_f32_e32 v24, v24, v22
	v_sub_f32_e32 v25, v25, v22
	v_mul_f32_e32 v24, v23, v24
	v_mul_f32_e32 v25, v23, v25
	v_fma_f32 v24, v72, v24, v186
	v_fma_f32 v25, v73, v25, v187
	v_cvt_pk_bf16_f32 v30, v24, v25
	v_lshlrev_b32_e32 v24, 16, v193
	v_and_b32_e32 v25, 0xffff0000, v193
	v_sub_f32_e32 v24, v24, v22
	v_sub_f32_e32 v25, v25, v22
	v_mul_f32_e32 v24, v23, v24
	v_mul_f32_e32 v25, v23, v25
	v_fma_f32 v24, v74, v24, v188
	v_fma_f32 v25, v75, v25, v189
	v_cvt_pk_bf16_f32 v31, v24, v25
	ds_write_b128 v176, v[28:31] offset:2048
	s_waitcnt lgkmcnt(3)
	v_lshlrev_b32_e32 v24, 16, v80
	v_and_b32_e32 v25, 0xffff0000, v80
	v_sub_f32_e32 v24, v24, v180
	v_sub_f32_e32 v25, v25, v180
	v_mul_f32_e32 v24, v181, v24
	v_mul_f32_e32 v25, v181, v25
	v_fma_f32 v24, v68, v24, v76
	v_fma_f32 v25, v69, v25, v77
	v_cvt_pk_bf16_f32 v28, v24, v25
	v_lshlrev_b32_e32 v24, 16, v81
	v_and_b32_e32 v25, 0xffff0000, v81
	v_sub_f32_e32 v24, v24, v180
	v_sub_f32_e32 v25, v25, v180
	v_mul_f32_e32 v24, v181, v24
	v_mul_f32_e32 v25, v181, v25
	v_fma_f32 v24, v70, v24, v78
	v_fma_f32 v25, v71, v25, v79
	v_cvt_pk_bf16_f32 v29, v24, v25
	v_lshlrev_b32_e32 v24, 16, v82
	v_and_b32_e32 v25, 0xffff0000, v82
	v_sub_f32_e32 v24, v24, v180
	v_sub_f32_e32 v25, v25, v180
	v_mul_f32_e32 v24, v181, v24
	v_mul_f32_e32 v25, v181, v25
	v_fma_f32 v24, v72, v24, v186
	v_fma_f32 v25, v73, v25, v187
	v_cvt_pk_bf16_f32 v30, v24, v25
	v_lshlrev_b32_e32 v24, 16, v83
	v_and_b32_e32 v25, 0xffff0000, v83
	v_sub_f32_e32 v24, v24, v180
	v_sub_f32_e32 v25, v25, v180
	v_mul_f32_e32 v24, v181, v24
	v_mul_f32_e32 v25, v181, v25
	v_fma_f32 v24, v74, v24, v188
	v_fma_f32 v25, v75, v25, v189
	v_cvt_pk_bf16_f32 v31, v24, v25
	ds_write_b128 v176, v[28:31] offset:11264
	s_waitcnt lgkmcnt(3)
	v_lshlrev_b32_e32 v24, 16, v84
	v_and_b32_e32 v25, 0xffff0000, v84
	v_sub_f32_e32 v24, v24, v182
	v_sub_f32_e32 v25, v25, v182
	v_mul_f32_e32 v24, v183, v24
	v_mul_f32_e32 v25, v183, v25
	v_fma_f32 v24, v68, v24, v76
	v_fma_f32 v25, v69, v25, v77
	v_cvt_pk_bf16_f32 v28, v24, v25
	v_lshlrev_b32_e32 v24, 16, v85
	v_and_b32_e32 v25, 0xffff0000, v85
	v_sub_f32_e32 v24, v24, v182
	v_sub_f32_e32 v25, v25, v182
	v_mul_f32_e32 v24, v183, v24
	v_mul_f32_e32 v25, v183, v25
	v_fma_f32 v24, v70, v24, v78
	v_fma_f32 v25, v71, v25, v79
	v_cvt_pk_bf16_f32 v29, v24, v25
	v_lshlrev_b32_e32 v24, 16, v86
	v_and_b32_e32 v25, 0xffff0000, v86
	v_sub_f32_e32 v24, v24, v182
	v_sub_f32_e32 v25, v25, v182
	v_mul_f32_e32 v24, v183, v24
	v_mul_f32_e32 v25, v183, v25
	v_fma_f32 v24, v72, v24, v186
	v_fma_f32 v25, v73, v25, v187
	v_cvt_pk_bf16_f32 v30, v24, v25
	v_lshlrev_b32_e32 v24, 16, v87
	v_and_b32_e32 v25, 0xffff0000, v87
	v_sub_f32_e32 v24, v24, v182
	v_sub_f32_e32 v25, v25, v182
	v_mul_f32_e32 v24, v183, v24
	v_mul_f32_e32 v25, v183, v25
	v_fma_f32 v24, v74, v24, v188
	v_fma_f32 v25, v75, v25, v189
	v_cvt_pk_bf16_f32 v31, v24, v25
	ds_write_b128 v176, v[28:31] offset:20480
	s_waitcnt lgkmcnt(3)
	v_lshlrev_b32_e32 v24, 16, v88
	v_and_b32_e32 v25, 0xffff0000, v88
	v_sub_f32_e32 v24, v24, v184
	v_sub_f32_e32 v25, v25, v184
	v_mul_f32_e32 v24, v185, v24
	v_mul_f32_e32 v25, v185, v25
	v_fma_f32 v24, v68, v24, v76
	v_fma_f32 v25, v69, v25, v77
	v_cvt_pk_bf16_f32 v28, v24, v25
	v_lshlrev_b32_e32 v24, 16, v89
	v_and_b32_e32 v25, 0xffff0000, v89
	v_sub_f32_e32 v24, v24, v184
	v_sub_f32_e32 v25, v25, v184
	v_mul_f32_e32 v24, v185, v24
	v_mul_f32_e32 v25, v185, v25
	v_fma_f32 v24, v70, v24, v78
	v_fma_f32 v25, v71, v25, v79
	v_cvt_pk_bf16_f32 v29, v24, v25
	v_lshlrev_b32_e32 v24, 16, v90
	v_and_b32_e32 v25, 0xffff0000, v90
	v_sub_f32_e32 v24, v24, v184
	v_sub_f32_e32 v25, v25, v184
	v_mul_f32_e32 v24, v185, v24
	v_mul_f32_e32 v25, v185, v25
	v_fma_f32 v24, v72, v24, v186
	v_fma_f32 v25, v73, v25, v187
	v_cvt_pk_bf16_f32 v30, v24, v25
	v_lshlrev_b32_e32 v24, 16, v91
	v_and_b32_e32 v25, 0xffff0000, v91
	v_sub_f32_e32 v24, v24, v184
	v_sub_f32_e32 v25, v25, v184
	v_mul_f32_e32 v24, v185, v24
	v_mul_f32_e32 v25, v185, v25
	v_fma_f32 v24, v74, v24, v188
	v_fma_f32 v25, v75, v25, v189
	v_cvt_pk_bf16_f32 v31, v24, v25
	ds_write_b128 v176, v[28:31] offset:29696
	s_add_u32 s4, s4, 0x100
	s_addc_u32 s5, s5, 0
	s_waitcnt lgkmcnt(0)
	s_barrier
; __device__ __forceinline__ float bf_lo(unsigned w) { return __uint_as_float(w << 16); }
; __device__ __forceinline__ float bf_hi(unsigned w) { return __uint_as_float(w & 0xffff0000u); }
; #define LAS __attribute__((address_space(3)))
; __device__ __forceinline__ void gate_unit(LAS unsigned char* lds, bf16_t* Zg, int ch, const bf16_t* wsb, const float* ln_g, const float* ln_b, const float* b_s, bool dostore = true) {
;     ...
;         for (int i = 0; i < 4; ++i) { const int p = tid + 512 * i, q = p >> 4, c = p & 15; const int col = g * 128 + c * 8;
;             const u32x4 w = *(const u32x4*)(Zc + (size_t)q * ZLD + COL_VB + col);
;             const float mean = stats[q * 2], rstd = stats[q * 2 + 1];
;             const f32x4 g0 = *(const f32x4*)(ln_g + col), g1 = *(const f32x4*)(ln_g + col + 4), b0 = *(const f32x4*)(ln_b + col), b1 = *(const f32x4*)(ln_b + col + 4);
;             float v[8] = {bf_lo(w.x), bf_hi(w.x), bf_lo(w.y), bf_hi(w.y), bf_lo(w.z), bf_hi(w.z), bf_lo(w.w), bf_hi(w.w)};
;             const float gg[8] = {g0.x, g0.y, g0.z, g0.w, g1.x, g1.y, g1.z, g1.w}, bb[8] = {b0.x, b0.y, b0.z, b0.w, b1.x, b1.y, b1.z, b1.w};
; #pragma unroll
;             for (int e = 0; e < 8; ++e) vnT[(c * 8 + e) * 136 + q] = (bf16_t)f2bf((v[e] - mean) * rstd * gg[e] + bb[e]); }
;         __syncthreads();
;         f32x16 acc[2]; acc[0] = f32x16{}; acc[1] = f32x16{};
;         const bf16_t* ap = wsb + (size_t)g * 16384 + (32 * pt + r32) * 128 + 8 * hi;
; #pragma unroll
;         for (int ks = 0; ks < 8; ++ks) { const bf16x8 a = *(const bf16x8*)(ap + 16 * ks);
; #pragma unroll
;             for (int j = 0; j < 2; ++j) { const bf16x8 b = *(const LAS bf16x8*)(vnT + (32 * (kt0 + j) + r32) * 136 + 16 * ks + 8 * hi);
;                 acc[j] = __builtin_amdgcn_mfma_f32_32x32x16_bf16(a, b, acc[j], 0, 0, 0); } }
;         LAS float* st = (LAS float*)(lds + 40960);
; #pragma unroll
;         for (int j = 0; j < 2; ++j)
; #pragma unroll
;             for (int r = 0; r < 16; ++r) { const int p = 32 * pt + crow(r, hi); st[p * 132 + 32 * (kt0 + j) + r32] = acc[j][r] + b_s[g * 128 + p]; }
;         __syncthreads();
; #pragma unroll
;         for (int i = 0; i < 4; ++i) { const int p = (tid >> 4) + 32 * i, c8 = (tid & 15) * 8; bf16_t* zr = Zc + (size_t)p * ZLD + g * 128 + c8;
;             const u32x4 uw = *(const u32x4*)(zr + COL_U), gw = *(const u32x4*)(zr + COL_GB);
	ds_read_b64_tr_b16 v[68:69], v177 offset:2048
	ds_read_b64_tr_b16 v[70:71], v177 offset:3200
	ds_read_b64_tr_b16 v[72:73], v177 offset:2112
	ds_read_b64_tr_b16 v[74:75], v177 offset:3264
	ds_read_b64_tr_b16 v[76:77], v177 offset:6656
	ds_read_b64_tr_b16 v[78:79], v177 offset:7808
	ds_read_b64_tr_b16 v[186:187], v177 offset:6720
	ds_read_b64_tr_b16 v[188:189], v177 offset:7872
	s_waitcnt lgkmcnt(4)
	v_mfma_f32_32x32x16_bf16 v[18:33], v[92:95], v[68:71], 0
	v_mfma_f32_32x32x16_bf16 v[2:17], v[92:95], v[72:75], 0
	ds_read_b64_tr_b16 v[68:69], v177 offset:11264
	ds_read_b64_tr_b16 v[70:71], v177 offset:12416
	ds_read_b64_tr_b16 v[72:73], v177 offset:11328
	ds_read_b64_tr_b16 v[74:75], v177 offset:12480
	s_waitcnt lgkmcnt(4)
	v_mfma_f32_32x32x16_bf16 v[18:33], v[96:99], v[76:79], v[18:33]
	v_mfma_f32_32x32x16_bf16 v[2:17], v[96:99], v[186:189], v[2:17]
	ds_read_b64_tr_b16 v[76:77], v177 offset:15872
	ds_read_b64_tr_b16 v[78:79], v177 offset:17024
	ds_read_b64_tr_b16 v[186:187], v177 offset:15936
	ds_read_b64_tr_b16 v[188:189], v177 offset:17088
	s_waitcnt lgkmcnt(4)
	v_mfma_f32_32x32x16_bf16 v[18:33], v[100:103], v[68:71], v[18:33]
	v_mfma_f32_32x32x16_bf16 v[2:17], v[100:103], v[72:75], v[2:17]
	ds_read_b64_tr_b16 v[68:69], v177 offset:20480
	ds_read_b64_tr_b16 v[70:71], v177 offset:21632
	ds_read_b64_tr_b16 v[72:73], v177 offset:20544
	ds_read_b64_tr_b16 v[74:75], v177 offset:21696
	s_waitcnt lgkmcnt(4)
	v_mfma_f32_32x32x16_bf16 v[18:33], v[104:107], v[76:79], v[18:33]
	v_mfma_f32_32x32x16_bf16 v[2:17], v[104:107], v[186:189], v[2:17]
	ds_read_b64_tr_b16 v[76:77], v177 offset:25088
	ds_read_b64_tr_b16 v[78:79], v177 offset:26240
	ds_read_b64_tr_b16 v[186:187], v177 offset:25152
	ds_read_b64_tr_b16 v[188:189], v177 offset:26304
	s_waitcnt lgkmcnt(4)
	v_mfma_f32_32x32x16_bf16 v[18:33], v[108:111], v[68:71], v[18:33]
	v_mfma_f32_32x32x16_bf16 v[2:17], v[108:111], v[72:75], v[2:17]
	ds_read_b64_tr_b16 v[68:69], v177 offset:29696
	ds_read_b64_tr_b16 v[70:71], v177 offset:30848
	ds_read_b64_tr_b16 v[72:73], v177 offset:29760
	ds_read_b64_tr_b16 v[74:75], v177 offset:30912
	s_waitcnt lgkmcnt(4)
	v_mfma_f32_32x32x16_bf16 v[18:33], v[112:115], v[76:79], v[18:33]
	v_mfma_f32_32x32x16_bf16 v[2:17], v[112:115], v[186:189], v[2:17]
	ds_read_b64_tr_b16 v[76:77], v177 offset:34304
	ds_read_b64_tr_b16 v[78:79], v177 offset:35456
	ds_read_b64_tr_b16 v[186:187], v177 offset:34368
	ds_read_b64_tr_b16 v[188:189], v177 offset:35520
	s_waitcnt lgkmcnt(4)
	v_mfma_f32_32x32x16_bf16 v[18:33], v[116:119], v[68:71], v[18:33]
	v_mfma_f32_32x32x16_bf16 v[2:17], v[116:119], v[72:75], v[2:17]
	s_waitcnt lgkmcnt(0)
	v_mfma_f32_32x32x16_bf16 v[18:33], v[120:123], v[76:79], v[18:33]
	v_mfma_f32_32x32x16_bf16 v[2:17], v[120:123], v[186:189], v[2:17]
	v_add_u32_e32 v35, 0xa000, v65
	s_waitcnt vmcnt(8)
	s_nop 9
	v_add_f32_e32 v18, v18, v126
	v_add_f32_e32 v19, v19, v127
	ds_write2_b32 v35, v18, v19 offset1:132
	v_add_f32_e32 v18, v20, v128
	v_add_f32_e32 v19, v21, v129
	v_add_u32_e32 v20, 0xa400, v65
	ds_write2_b32 v20, v18, v19 offset0:8 offset1:140
	v_add_u32_e32 v35, 0xb000, v65
	v_add_f32_e32 v2, v2, v126
	v_add_f32_e32 v3, v3, v127
	v_add_f32_e32 v22, v22, v130
	v_add_f32_e32 v23, v23, v131
	ds_write2_b32 v35, v22, v23 offset0:32 offset1:164
	v_add_f32_e32 v22, v24, v132
	v_add_f32_e32 v23, v25, v133
	v_add_u32_e32 v24, 0xb400, v65
	ds_write2_b32 v24, v22, v23 offset0:40 offset1:172
	v_add_u32_e32 v35, 0xc000, v65
	v_add_f32_e32 v26, v26, v134
	v_add_f32_e32 v27, v27, v135
	ds_write2_b32 v35, v26, v27 offset0:64 offset1:196
	v_add_f32_e32 v26, v28, v136
	v_add_f32_e32 v27, v29, v137
	v_add_u32_e32 v28, 0xc400, v65
	ds_write2_b32 v28, v26, v27 offset0:72 offset1:204
	v_add_u32_e32 v35, 0xd000, v65
	v_add_f32_e32 v30, v30, v138
	v_add_f32_e32 v31, v31, v139
	ds_write2_b32 v35, v30, v31 offset0:96 offset1:228
	v_add_f32_e32 v30, v32, v140
	v_add_f32_e32 v31, v33, v141
	v_add_u32_e32 v32, 0xd400, v65
	ds_write2_b32 v32, v30, v31 offset0:104 offset1:236
	v_add_u32_e32 v30, 0xa000, v66
	ds_write2_b32 v30, v2, v3 offset1:132
	v_add_f32_e32 v2, v4, v128
	v_add_f32_e32 v3, v5, v129
	v_add_u32_e32 v4, 0xa400, v66
	ds_write2_b32 v4, v2, v3 offset0:8 offset1:140
	v_add_f32_e32 v2, v6, v130
	v_add_f32_e32 v3, v7, v131
	v_add_u32_e32 v4, 0xb000, v66
	ds_write2_b32 v4, v2, v3 offset0:32 offset1:164
	v_add_f32_e32 v2, v8, v132
	v_add_f32_e32 v3, v9, v133
	v_add_u32_e32 v4, 0xb400, v66
	ds_write2_b32 v4, v2, v3 offset0:40 offset1:172
	v_add_f32_e32 v2, v10, v134
	v_add_f32_e32 v3, v11, v135
	v_add_u32_e32 v4, 0xc000, v66
	ds_write2_b32 v4, v2, v3 offset0:64 offset1:196
	v_add_f32_e32 v2, v12, v136
	v_add_f32_e32 v3, v13, v137
	v_add_u32_e32 v4, 0xc400, v66
	ds_write2_b32 v4, v2, v3 offset0:72 offset1:204
	v_add_f32_e32 v2, v14, v138
	v_add_f32_e32 v3, v15, v139
	v_add_u32_e32 v4, 0xd000, v66
	v_add_co_u32_e32 v6, vcc, s10, v58
	ds_write2_b32 v4, v2, v3 offset0:96 offset1:228
	v_add_f32_e32 v2, v16, v140
	v_add_f32_e32 v3, v17, v141
	v_add_u32_e32 v4, 0xd400, v66
	v_addc_co_u32_e32 v7, vcc, 0, v59, vcc
	ds_write2_b32 v4, v2, v3 offset0:104 offset1:236
	v_lshl_add_u64 v[174:175], v[46:47], 0, s[4:5]
	v_add_co_u32_e32 v174, vcc, 0x5a02000, v174
	s_nop 1
	v_addc_co_u32_e32 v175, vcc, 0, v175, vcc
	global_load_dwordx4 v[190:193], v[174:175], off offset:2048
	v_lshl_add_u64 v[124:125], v[56:57], 0, s[4:5]
	global_load_dwordx4 v[80:83], v[124:125], off
	v_lshl_add_u64 v[124:125], v[52:53], 0, s[4:5]
	global_load_dwordx4 v[84:87], v[124:125], off
	v_lshl_add_u64 v[124:125], v[48:49], 0, s[4:5]
	global_load_dwordx4 v[88:91], v[124:125], off
	global_load_dwordx4 v[72:75], v[50:51], off
	global_load_dwordx4 v[68:71], v[50:51], off offset:-16
	global_load_dwordx4 v[186:189], v[54:55], off
	global_load_dwordx4 v[76:79], v[54:55], off offset:-16
	global_load_dwordx4 v[92:95], v[44:45], off
	global_load_dwordx4 v[96:99], v[44:45], off offset:32
	global_load_dwordx4 v[100:103], v[44:45], off offset:64
	global_load_dwordx4 v[104:107], v[44:45], off offset:96
	global_load_dwordx4 v[108:111], v[44:45], off offset:128
	global_load_dwordx4 v[112:115], v[44:45], off offset:160
	global_load_dwordx4 v[116:119], v[44:45], off offset:192
	global_load_dwordx4 v[120:123], v[44:45], off offset:224
	v_ashrrev_i32_e32 v35, 31, v34
	v_lshl_add_u64 v[124:125], v[34:35], 2, s[20:21]
	global_load_dwordx4 v[126:129], v[124:125], off
	global_load_dwordx4 v[130:133], v[124:125], off offset:32
	global_load_dwordx4 v[134:137], v[124:125], off offset:64
	global_load_dwordx4 v[138:141], v[124:125], off offset:96
	s_cmpk_lt_u32 s4, 0x700
	s_cselect_b32 s46, 0x200, 0
	s_mov_b32 s47, 0
	v_lshl_add_u64 v[50:51], v[50:51], 0, s[46:47]
	v_lshl_add_u64 v[54:55], v[54:55], 0, s[46:47]
	s_cselect_b32 s46, 0x80, 0
	v_add_u32_e32 v34, s46, v34
	v_lshl_add_u64 v[44:45], v[44:45], 0, s[16:17]
	s_waitcnt lgkmcnt(0)
	s_barrier
; __device__ __forceinline__ unsigned cvt_pk_bf16(float lo, float hi) { f32x2 v = {lo, hi}; bf16x2_t b = __builtin_convertvector(v, bf16x2_t); return __builtin_bit_cast(unsigned, b); }
; __device__ __forceinline__ float bf_lo(unsigned w) { return __uint_as_float(w << 16); }
; __device__ __forceinline__ float bf_hi(unsigned w) { return __uint_as_float(w & 0xffff0000u); }
; __device__ __forceinline__ float sigmoidf_fast(float x) { return __builtin_amdgcn_rcpf(1.0f + __builtin_amdgcn_exp2f(-1.4426950408889634f * x)); }
; #define LAS __attribute__((address_space(3)))
; __device__ __forceinline__ void gate_unit(LAS unsigned char* lds, bf16_t* Zg, int ch, const bf16_t* wsb, const float* ln_g, const float* ln_b, const float* b_s, bool dostore = true) {
;     ...
; #pragma unroll
;         for (int i = 0; i < 4; ++i) { const int p = (tid >> 4) + 32 * i, c8 = (tid & 15) * 8; bf16_t* zr = Zc + (size_t)p * ZLD + g * 128 + c8;
;             const u32x4 uw = *(const u32x4*)(zr + COL_U), gw = *(const u32x4*)(zr + COL_GB);
;             const f32x4 s0 = *(const LAS f32x4*)(st + p * 132 + c8), s1 = *(const LAS f32x4*)(st + p * 132 + c8 + 4);
;             const float sv[8] = {s0.x, s0.y, s0.z, s0.w, s1.x, s1.y, s1.z, s1.w}; u32x4 ow;
; #pragma unroll
;             for (int e = 0; e < 4; ++e) { const float u0 = bf_lo(uw[e]), u1 = bf_hi(uw[e]), g0 = bf_lo(gw[e]), g1 = bf_hi(gw[e]);
;                 ow[e] = cvt_pk_bf16(u0 * sv[2 * e] * g0 * sigmoidf_fast(g0), u1 * sv[2 * e + 1] * g1 * sigmoidf_fast(g1)); }
;             if (dostore) *(u32x4*)(zr + COL_U) = ow; }
	s_waitcnt vmcnt(30)
	v_mov_b64_e32 v[2:3], v[142:143]
	v_mov_b64_e32 v[4:5], v[144:145]
	v_add_u32_e32 v24, v37, v39
	v_mov_b64_e32 v[6:7], v[146:147]
	v_mov_b64_e32 v[8:9], v[148:149]
	v_add_co_u32_e32 v124, vcc, 0x1000, v174
	s_nop 1
	v_addc_co_u32_e32 v125, vcc, 0, v175, vcc
	global_load_dwordx4 v[142:145], v[124:125], off offset:-4096
	global_load_dwordx4 v[146:149], v[124:125], off
	ds_read_b128 v[10:13], v24 offset:40960
	ds_read_b128 v[14:17], v24 offset:40976
	s_mov_b32 s10, 0x5a92000
	v_lshlrev_b32_e32 v18, 16, v2
	v_and_b32_e32 v19, 0xffff0000, v2
	v_lshlrev_b32_e32 v20, 16, v6
	v_mul_f32_e32 v2, 0xbfb8aa3b, v20
	v_exp_f32_e32 v2, v2
	v_and_b32_e32 v21, 0xffff0000, v6
	s_waitcnt lgkmcnt(1)
	v_pk_mul_f32 v[10:11], v[10:11], v[18:19]
	v_lshlrev_b32_e32 v6, 16, v7
	v_add_f32_e32 v2, 1.0, v2
	v_rcp_f32_e32 v22, v2
	v_mul_f32_e32 v2, 0xbfb8aa3b, v21
	v_exp_f32_e32 v2, v2
	v_pk_mul_f32 v[10:11], v[10:11], v[20:21]
	v_and_b32_e32 v7, 0xffff0000, v7
	v_add_f32_e32 v2, 1.0, v2
	v_rcp_f32_e32 v23, v2
	s_nop 0
	v_pk_mul_f32 v[10:11], v[10:11], v[22:23]
	s_nop 0
	v_cvt_pk_bf16_f32 v2, v10, v11
	v_lshlrev_b32_e32 v10, 16, v3
	v_and_b32_e32 v11, 0xffff0000, v3
	v_mul_f32_e32 v3, 0xbfb8aa3b, v6
	v_exp_f32_e32 v3, v3
	v_pk_mul_f32 v[10:11], v[12:13], v[10:11]
	v_add_f32_e32 v3, 1.0, v3
	v_rcp_f32_e32 v18, v3
	v_mul_f32_e32 v3, 0xbfb8aa3b, v7
	v_exp_f32_e32 v3, v3
	v_pk_mul_f32 v[10:11], v[10:11], v[6:7]
	v_add_f32_e32 v3, 1.0, v3
	v_rcp_f32_e32 v19, v3
	s_nop 0
	v_pk_mul_f32 v[6:7], v[10:11], v[18:19]
	v_lshlrev_b32_e32 v10, 16, v8
	v_cvt_pk_bf16_f32 v3, v6, v7
	v_lshlrev_b32_e32 v6, 16, v4
	v_and_b32_e32 v7, 0xffff0000, v4
	v_mul_f32_e32 v4, 0xbfb8aa3b, v10
	v_exp_f32_e32 v4, v4
	v_and_b32_e32 v11, 0xffff0000, v8
	s_waitcnt lgkmcnt(0)
	v_pk_mul_f32 v[6:7], v[14:15], v[6:7]
	v_lshlrev_b32_e32 v8, 16, v9
	v_add_f32_e32 v4, 1.0, v4
	v_rcp_f32_e32 v12, v4
	v_mul_f32_e32 v4, 0xbfb8aa3b, v11
	v_exp_f32_e32 v4, v4
	v_pk_mul_f32 v[6:7], v[6:7], v[10:11]
	v_and_b32_e32 v9, 0xffff0000, v9
	v_add_co_u32_e32 v18, vcc, s10, v58
	v_add_f32_e32 v4, 1.0, v4
	v_rcp_f32_e32 v13, v4
	v_addc_co_u32_e32 v19, vcc, 0, v59, vcc
	s_mov_b32 s10, 0x5a93000
	v_pk_mul_f32 v[6:7], v[6:7], v[12:13]
	s_nop 0
	v_cvt_pk_bf16_f32 v4, v6, v7
	v_lshlrev_b32_e32 v6, 16, v5
	v_and_b32_e32 v7, 0xffff0000, v5
	v_mul_f32_e32 v5, 0xbfb8aa3b, v8
	v_exp_f32_e32 v5, v5
	v_pk_mul_f32 v[6:7], v[16:17], v[6:7]
	v_add_f32_e32 v5, 1.0, v5
	v_rcp_f32_e32 v10, v5
	v_mul_f32_e32 v5, 0xbfb8aa3b, v9
	v_exp_f32_e32 v5, v5
	v_pk_mul_f32 v[6:7], v[6:7], v[8:9]
	v_add_f32_e32 v5, 1.0, v5
	v_rcp_f32_e32 v11, v5
	s_nop 0
	v_pk_mul_f32 v[6:7], v[6:7], v[10:11]
	s_nop 0
	v_cvt_pk_bf16_f32 v5, v6, v7
	v_add_co_u32_e32 v6, vcc, s10, v58
	global_store_dwordx4 v[60:61], v[2:5], off
	s_nop 0
	v_addc_co_u32_e32 v7, vcc, 0, v59, vcc
	s_waitcnt vmcnt(30)
	v_mov_b64_e32 v[2:3], v[150:151]
	v_mov_b64_e32 v[4:5], v[152:153]
	s_nop 0
	v_mov_b64_e32 v[6:7], v[154:155]
	v_mov_b64_e32 v[8:9], v[156:157]
	v_add_co_u32_e32 v124, vcc, 0x91000, v174
	s_nop 1
	v_addc_co_u32_e32 v125, vcc, 0, v175, vcc
	global_load_dwordx4 v[150:153], v[124:125], off offset:-4096
	global_load_dwordx4 v[154:157], v[124:125], off
	ds_read_b128 v[10:13], v24 offset:57856
	ds_read_b128 v[14:17], v24 offset:57872
	s_mov_b32 s10, 0x5b22000
	v_lshlrev_b32_e32 v20, 16, v2
	v_lshlrev_b32_e32 v22, 16, v6
	v_and_b32_e32 v21, 0xffff0000, v2
	v_mul_f32_e32 v2, 0xbfb8aa3b, v22
	v_exp_f32_e32 v2, v2
	v_and_b32_e32 v23, 0xffff0000, v6
	s_waitcnt lgkmcnt(1)
	v_pk_mul_f32 v[10:11], v[10:11], v[20:21]
	v_lshlrev_b32_e32 v6, 16, v7
	v_add_f32_e32 v2, 1.0, v2
	v_rcp_f32_e32 v24, v2
	v_mul_f32_e32 v2, 0xbfb8aa3b, v23
	v_exp_f32_e32 v2, v2
	v_pk_mul_f32 v[10:11], v[10:11], v[22:23]
	v_and_b32_e32 v7, 0xffff0000, v7
	v_add_f32_e32 v2, 1.0, v2
	v_rcp_f32_e32 v25, v2
	s_nop 0
	v_pk_mul_f32 v[10:11], v[10:11], v[24:25]
	s_nop 0
	v_cvt_pk_bf16_f32 v2, v10, v11
	v_lshlrev_b32_e32 v10, 16, v3
	v_and_b32_e32 v11, 0xffff0000, v3
	v_mul_f32_e32 v3, 0xbfb8aa3b, v6
	v_exp_f32_e32 v3, v3
	v_pk_mul_f32 v[10:11], v[12:13], v[10:11]
	v_add_f32_e32 v3, 1.0, v3
	v_rcp_f32_e32 v20, v3
	v_mul_f32_e32 v3, 0xbfb8aa3b, v7
	v_exp_f32_e32 v3, v3
	v_pk_mul_f32 v[10:11], v[10:11], v[6:7]
	v_add_f32_e32 v3, 1.0, v3
	v_rcp_f32_e32 v21, v3
	s_nop 0
	v_pk_mul_f32 v[6:7], v[10:11], v[20:21]
	v_lshlrev_b32_e32 v10, 16, v8
	v_cvt_pk_bf16_f32 v3, v6, v7
	v_lshlrev_b32_e32 v6, 16, v4
	v_and_b32_e32 v7, 0xffff0000, v4
	v_mul_f32_e32 v4, 0xbfb8aa3b, v10
	v_exp_f32_e32 v4, v4
	v_and_b32_e32 v11, 0xffff0000, v8
	s_waitcnt lgkmcnt(0)
	v_pk_mul_f32 v[6:7], v[14:15], v[6:7]
	v_lshlrev_b32_e32 v8, 16, v9
	v_add_f32_e32 v4, 1.0, v4
	v_rcp_f32_e32 v12, v4
	v_mul_f32_e32 v4, 0xbfb8aa3b, v11
	v_exp_f32_e32 v4, v4
	v_pk_mul_f32 v[6:7], v[6:7], v[10:11]
	v_and_b32_e32 v9, 0xffff0000, v9
	v_add_f32_e32 v4, 1.0, v4
	v_rcp_f32_e32 v13, v4
	s_nop 0
	v_pk_mul_f32 v[6:7], v[6:7], v[12:13]
	s_nop 0
	v_cvt_pk_bf16_f32 v4, v6, v7
	v_lshlrev_b32_e32 v6, 16, v5
	v_and_b32_e32 v7, 0xffff0000, v5
	v_mul_f32_e32 v5, 0xbfb8aa3b, v8
	v_exp_f32_e32 v5, v5
	v_pk_mul_f32 v[6:7], v[16:17], v[6:7]
	v_add_f32_e32 v5, 1.0, v5
	v_rcp_f32_e32 v10, v5
	v_mul_f32_e32 v5, 0xbfb8aa3b, v9
	v_exp_f32_e32 v5, v5
	v_pk_mul_f32 v[6:7], v[6:7], v[8:9]
	v_add_f32_e32 v5, 1.0, v5
	v_rcp_f32_e32 v11, v5
	s_nop 0
	v_pk_mul_f32 v[6:7], v[6:7], v[10:11]
	s_nop 0
	v_cvt_pk_bf16_f32 v5, v6, v7
	global_store_dwordx4 v[18:19], v[2:5], off
	v_add_co_u32_e32 v18, vcc, s10, v58
	s_mov_b32 s10, 0x5b23000
	s_nop 0
	v_addc_co_u32_e32 v19, vcc, 0, v59, vcc
	v_add_co_u32_e32 v6, vcc, s10, v58
	s_mov_b32 s10, 0x5bb2000
	s_nop 0
	v_addc_co_u32_e32 v7, vcc, 0, v59, vcc
	s_waitcnt vmcnt(30)
; __device__ __forceinline__ unsigned cvt_pk_bf16(float lo, float hi) { f32x2 v = {lo, hi}; bf16x2_t b = __builtin_convertvector(v, bf16x2_t); return __builtin_bit_cast(unsigned, b); }
; __device__ __forceinline__ float bf_lo(unsigned w) { return __uint_as_float(w << 16); }
; __device__ __forceinline__ float bf_hi(unsigned w) { return __uint_as_float(w & 0xffff0000u); }
; __device__ __forceinline__ float sigmoidf_fast(float x) { return __builtin_amdgcn_rcpf(1.0f + __builtin_amdgcn_exp2f(-1.4426950408889634f * x)); }
; #define LAS __attribute__((address_space(3)))
; __device__ __forceinline__ void gate_unit(LAS unsigned char* lds, bf16_t* Zg, int ch, const bf16_t* wsb, const float* ln_g, const float* ln_b, const float* b_s, bool dostore = true) {
;     ...
; #pragma unroll
;         for (int i = 0; i < 4; ++i) { const int p = (tid >> 4) + 32 * i, c8 = (tid & 15) * 8; bf16_t* zr = Zc + (size_t)p * ZLD + g * 128 + c8;
;             const u32x4 uw = *(const u32x4*)(zr + COL_U), gw = *(const u32x4*)(zr + COL_GB);
;             const f32x4 s0 = *(const LAS f32x4*)(st + p * 132 + c8), s1 = *(const LAS f32x4*)(st + p * 132 + c8 + 4);
;             const float sv[8] = {s0.x, s0.y, s0.z, s0.w, s1.x, s1.y, s1.z, s1.w}; u32x4 ow;
; #pragma unroll
;             for (int e = 0; e < 4; ++e) { const float u0 = bf_lo(uw[e]), u1 = bf_hi(uw[e]), g0 = bf_lo(gw[e]), g1 = bf_hi(gw[e]);
;                 ow[e] = cvt_pk_bf16(u0 * sv[2 * e] * g0 * sigmoidf_fast(g0), u1 * sv[2 * e + 1] * g1 * sigmoidf_fast(g1)); }
;             if (dostore) *(u32x4*)(zr + COL_U) = ow; }
;         __syncthreads();
;     }
	v_mov_b64_e32 v[2:3], v[158:159]
	v_mov_b64_e32 v[4:5], v[160:161]
	s_nop 0
	v_mov_b64_e32 v[6:7], v[162:163]
	v_mov_b64_e32 v[8:9], v[164:165]
	v_add_co_u32_e32 v124, vcc, 0x121000, v174
	s_nop 1
	v_addc_co_u32_e32 v125, vcc, 0, v175, vcc
	global_load_dwordx4 v[158:161], v[124:125], off offset:-4096
	global_load_dwordx4 v[162:165], v[124:125], off
	ds_read_b128 v[10:13], v67 offset:40960
	ds_read_b128 v[14:17], v67 offset:40976
	v_lshlrev_b32_e32 v20, 16, v2
	v_lshlrev_b32_e32 v22, 16, v6
	v_and_b32_e32 v21, 0xffff0000, v2
	v_mul_f32_e32 v2, 0xbfb8aa3b, v22
	v_exp_f32_e32 v2, v2
	v_and_b32_e32 v23, 0xffff0000, v6
	s_waitcnt lgkmcnt(1)
	v_pk_mul_f32 v[10:11], v[10:11], v[20:21]
	v_lshlrev_b32_e32 v6, 16, v7
	v_add_f32_e32 v2, 1.0, v2
	v_rcp_f32_e32 v24, v2
	v_mul_f32_e32 v2, 0xbfb8aa3b, v23
	v_exp_f32_e32 v2, v2
	v_pk_mul_f32 v[10:11], v[10:11], v[22:23]
	v_and_b32_e32 v7, 0xffff0000, v7
	v_add_f32_e32 v2, 1.0, v2
	v_rcp_f32_e32 v25, v2
	s_nop 0
	v_pk_mul_f32 v[10:11], v[10:11], v[24:25]
	s_nop 0
	v_cvt_pk_bf16_f32 v2, v10, v11
	v_lshlrev_b32_e32 v10, 16, v3
	v_and_b32_e32 v11, 0xffff0000, v3
	v_mul_f32_e32 v3, 0xbfb8aa3b, v6
	v_exp_f32_e32 v3, v3
	v_pk_mul_f32 v[10:11], v[12:13], v[10:11]
	v_add_f32_e32 v3, 1.0, v3
	v_rcp_f32_e32 v20, v3
	v_mul_f32_e32 v3, 0xbfb8aa3b, v7
	v_exp_f32_e32 v3, v3
	v_pk_mul_f32 v[10:11], v[10:11], v[6:7]
	v_add_f32_e32 v3, 1.0, v3
	v_rcp_f32_e32 v21, v3
	s_nop 0
	v_pk_mul_f32 v[6:7], v[10:11], v[20:21]
	v_lshlrev_b32_e32 v10, 16, v8
	v_cvt_pk_bf16_f32 v3, v6, v7
	v_lshlrev_b32_e32 v6, 16, v4
	v_and_b32_e32 v7, 0xffff0000, v4
	v_mul_f32_e32 v4, 0xbfb8aa3b, v10
	v_exp_f32_e32 v4, v4
	v_and_b32_e32 v11, 0xffff0000, v8
	s_waitcnt lgkmcnt(0)
	v_pk_mul_f32 v[6:7], v[14:15], v[6:7]
	v_lshlrev_b32_e32 v8, 16, v9
	v_add_f32_e32 v4, 1.0, v4
	v_rcp_f32_e32 v12, v4
	v_mul_f32_e32 v4, 0xbfb8aa3b, v11
	v_exp_f32_e32 v4, v4
	v_pk_mul_f32 v[6:7], v[6:7], v[10:11]
	v_and_b32_e32 v9, 0xffff0000, v9
	v_add_f32_e32 v4, 1.0, v4
	v_rcp_f32_e32 v13, v4
	s_nop 0
	v_pk_mul_f32 v[6:7], v[6:7], v[12:13]
	s_nop 0
	v_cvt_pk_bf16_f32 v4, v6, v7
	v_lshlrev_b32_e32 v6, 16, v5
	v_and_b32_e32 v7, 0xffff0000, v5
	v_mul_f32_e32 v5, 0xbfb8aa3b, v8
	v_exp_f32_e32 v5, v5
	v_pk_mul_f32 v[6:7], v[16:17], v[6:7]
	v_add_f32_e32 v5, 1.0, v5
	v_rcp_f32_e32 v10, v5
	v_mul_f32_e32 v5, 0xbfb8aa3b, v9
	v_exp_f32_e32 v5, v5
	v_pk_mul_f32 v[6:7], v[6:7], v[8:9]
	v_add_f32_e32 v5, 1.0, v5
	v_rcp_f32_e32 v11, v5
	s_nop 0
	v_pk_mul_f32 v[6:7], v[6:7], v[10:11]
	s_nop 0
	v_cvt_pk_bf16_f32 v5, v6, v7
	global_store_dwordx4 v[18:19], v[2:5], off
	v_add_co_u32_e32 v18, vcc, s10, v58
	s_mov_b32 s10, 0x5bb3000
	s_nop 0
	v_addc_co_u32_e32 v19, vcc, 0, v59, vcc
	v_add_co_u32_e32 v6, vcc, s10, v58
	s_nop 1
	v_addc_co_u32_e32 v7, vcc, 0, v59, vcc
	s_waitcnt vmcnt(30)
	v_mov_b64_e32 v[2:3], v[166:167]
	v_mov_b64_e32 v[4:5], v[168:169]
	s_nop 0
	v_mov_b64_e32 v[6:7], v[170:171]
	v_mov_b64_e32 v[8:9], v[172:173]
	v_add_co_u32_e32 v124, vcc, 0x1b1000, v174
	s_nop 1
	v_addc_co_u32_e32 v125, vcc, 0, v175, vcc
	global_load_dwordx4 v[166:169], v[124:125], off offset:-4096
	global_load_dwordx4 v[170:173], v[124:125], off
	ds_read_b128 v[10:13], v67 offset:57856
	ds_read_b128 v[14:17], v67 offset:57872
	v_lshlrev_b32_e32 v20, 16, v2
	v_lshlrev_b32_e32 v22, 16, v6
	v_and_b32_e32 v21, 0xffff0000, v2
	v_mul_f32_e32 v2, 0xbfb8aa3b, v22
	v_exp_f32_e32 v2, v2
	v_and_b32_e32 v23, 0xffff0000, v6
	s_waitcnt lgkmcnt(1)
	v_pk_mul_f32 v[10:11], v[10:11], v[20:21]
	v_lshlrev_b32_e32 v6, 16, v7
	v_add_f32_e32 v2, 1.0, v2
	v_rcp_f32_e32 v24, v2
	v_mul_f32_e32 v2, 0xbfb8aa3b, v23
	v_exp_f32_e32 v2, v2
	v_pk_mul_f32 v[10:11], v[10:11], v[22:23]
	v_and_b32_e32 v7, 0xffff0000, v7
	v_add_f32_e32 v2, 1.0, v2
	v_rcp_f32_e32 v25, v2
	s_nop 0
	v_pk_mul_f32 v[10:11], v[10:11], v[24:25]
	s_nop 0
	v_cvt_pk_bf16_f32 v2, v10, v11
	v_lshlrev_b32_e32 v10, 16, v3
	v_and_b32_e32 v11, 0xffff0000, v3
	v_mul_f32_e32 v3, 0xbfb8aa3b, v6
	v_exp_f32_e32 v3, v3
	v_pk_mul_f32 v[10:11], v[12:13], v[10:11]
	v_add_f32_e32 v3, 1.0, v3
	v_rcp_f32_e32 v20, v3
	v_mul_f32_e32 v3, 0xbfb8aa3b, v7
	v_exp_f32_e32 v3, v3
	v_pk_mul_f32 v[10:11], v[10:11], v[6:7]
	v_add_f32_e32 v3, 1.0, v3
	v_rcp_f32_e32 v21, v3
	s_nop 0
	v_pk_mul_f32 v[6:7], v[10:11], v[20:21]
	v_lshlrev_b32_e32 v10, 16, v8
	v_cvt_pk_bf16_f32 v3, v6, v7
	v_lshlrev_b32_e32 v6, 16, v4
	v_and_b32_e32 v7, 0xffff0000, v4
	v_mul_f32_e32 v4, 0xbfb8aa3b, v10
	v_exp_f32_e32 v4, v4
	v_and_b32_e32 v11, 0xffff0000, v8
	s_waitcnt lgkmcnt(0)
	v_pk_mul_f32 v[6:7], v[14:15], v[6:7]
	v_lshlrev_b32_e32 v8, 16, v9
	v_add_f32_e32 v4, 1.0, v4
	v_rcp_f32_e32 v12, v4
	v_mul_f32_e32 v4, 0xbfb8aa3b, v11
	v_exp_f32_e32 v4, v4
	v_pk_mul_f32 v[6:7], v[6:7], v[10:11]
	v_and_b32_e32 v9, 0xffff0000, v9
	v_add_f32_e32 v4, 1.0, v4
	v_rcp_f32_e32 v13, v4
	s_nop 0
	v_pk_mul_f32 v[6:7], v[6:7], v[12:13]
	s_nop 0
	v_cvt_pk_bf16_f32 v4, v6, v7
	v_lshlrev_b32_e32 v6, 16, v5
	v_and_b32_e32 v7, 0xffff0000, v5
	v_mul_f32_e32 v5, 0xbfb8aa3b, v8
	v_exp_f32_e32 v5, v5
	v_pk_mul_f32 v[6:7], v[16:17], v[6:7]
	v_add_f32_e32 v5, 1.0, v5
	v_rcp_f32_e32 v10, v5
	v_mul_f32_e32 v5, 0xbfb8aa3b, v9
	v_exp_f32_e32 v5, v5
	v_pk_mul_f32 v[6:7], v[6:7], v[8:9]
	v_add_f32_e32 v5, 1.0, v5
	v_rcp_f32_e32 v11, v5
	s_nop 0
	v_pk_mul_f32 v[6:7], v[6:7], v[10:11]
	s_nop 0
	v_cvt_pk_bf16_f32 v5, v6, v7
	global_store_dwordx4 v[18:19], v[2:5], off
	s_cmpk_lg_i32 s4, 0x800
	s_barrier
	s_cbranch_scc1 .LBB0_183
	s_waitcnt vmcnt(0)
	s_add_i32 s15, s15, s3
	s_add_u32 s12, s12, s24
	s_addc_u32 s13, s13, s18
	s_add_u32 s8, s8, s24
	s_addc_u32 s9, s9, s18
	s_add_u32 s6, s6, s24
	s_addc_u32 s7, s7, s18
	s_cmpk_gt_i32 s15, 0xff
	s_cbranch_scc0 .LBB0_178
